# v22 with the static priority raise given to the leading wave half instead of the trailing half
# baseline (speedup 1.0000x reference)
; #define PG8_BAR __builtin_amdgcn_s_barrier()
; template <class Epi, class Sched>
; __device__ __forceinline__ void gemm_phase(LAS unsigned char* lds, const GemmP g, const Sched& S, const Epi& E, int tid) {
;     ...
; #pragma unroll
;         for (int a = 0; a < 2; ++a)
; #pragma unroll
;             for (int b = 0; b < 2; ++b)
; #pragma unroll
;                 for (int m = 0; m < 4; ++m)
; #pragma unroll
;                     for (int n = 0; n < 2; ++n) acc[a][b][m][n] = (f32x4){0.f, 0.f, 0.f, 0.f};
;         cur = nxt; cA = nA; cB = nB; ++ui;
;         if (wr == 1) PG8_BAR;
.LBB0_165:
	s_add_u32 s71, s44, 0x100
	s_addc_u32 s72, s45, 0
	s_add_u32 s4, s4, 0x40080
	v_mov_b32_e32 v0, 0
	s_addc_u32 s5, s5, 0
	s_mov_b32 s73, -2
	v_mov_b32_e32 v1, v0
	v_mov_b32_e32 v2, v0
	v_mov_b32_e32 v3, v0
	v_mov_b32_e32 v4, v0
	v_mov_b32_e32 v5, v0
	v_mov_b32_e32 v6, v0
	v_mov_b32_e32 v7, v0
	v_mov_b32_e32 v16, v0
	v_mov_b32_e32 v17, v0
	v_mov_b32_e32 v18, v0
	v_mov_b32_e32 v19, v0
	v_mov_b32_e32 v20, v0
	v_mov_b32_e32 v21, v0
	v_mov_b32_e32 v22, v0
	v_mov_b32_e32 v23, v0
	v_mov_b32_e32 v32, v0
	v_mov_b32_e32 v33, v0
	v_mov_b32_e32 v34, v0
	v_mov_b32_e32 v35, v0
	v_mov_b32_e32 v36, v0
	v_mov_b32_e32 v37, v0
	v_mov_b32_e32 v38, v0
	v_mov_b32_e32 v39, v0
	v_mov_b32_e32 v48, v0
	v_mov_b32_e32 v49, v0
	v_mov_b32_e32 v50, v0
	v_mov_b32_e32 v51, v0
	v_mov_b32_e32 v52, v0
	v_mov_b32_e32 v53, v0
	v_mov_b32_e32 v54, v0
	v_mov_b32_e32 v55, v0
	v_mov_b32_e32 v8, v0
	v_mov_b32_e32 v9, v0
	v_mov_b32_e32 v10, v0
	v_mov_b32_e32 v11, v0
	v_mov_b32_e32 v12, v0
	v_mov_b32_e32 v13, v0
	v_mov_b32_e32 v14, v0
	v_mov_b32_e32 v15, v0
	v_mov_b32_e32 v24, v0
	v_mov_b32_e32 v25, v0
	v_mov_b32_e32 v26, v0
	v_mov_b32_e32 v27, v0
	v_mov_b32_e32 v28, v0
	v_mov_b32_e32 v29, v0
	v_mov_b32_e32 v30, v0
	v_mov_b32_e32 v31, v0
	v_mov_b32_e32 v40, v0
	v_mov_b32_e32 v41, v0
	v_mov_b32_e32 v42, v0
	v_mov_b32_e32 v43, v0
	v_mov_b32_e32 v44, v0
	v_mov_b32_e32 v45, v0
	v_mov_b32_e32 v46, v0
	v_mov_b32_e32 v47, v0
	v_mov_b32_e32 v56, v0
	v_mov_b32_e32 v57, v0
	v_mov_b32_e32 v58, v0
	v_mov_b32_e32 v59, v0
	v_mov_b32_e32 v60, v0
	v_mov_b32_e32 v61, v0
	v_mov_b32_e32 v62, v0
	v_mov_b32_e32 v63, v0
	v_mov_b32_e32 v64, v0
	v_mov_b32_e32 v65, v0
	v_mov_b32_e32 v66, v0
	v_mov_b32_e32 v67, v0
	v_mov_b32_e32 v68, v0
	v_mov_b32_e32 v69, v0
	v_mov_b32_e32 v70, v0
	v_mov_b32_e32 v71, v0
	v_mov_b32_e32 v80, v0
	v_mov_b32_e32 v81, v0
	v_mov_b32_e32 v82, v0
	v_mov_b32_e32 v83, v0
	v_mov_b32_e32 v84, v0
	v_mov_b32_e32 v85, v0
	v_mov_b32_e32 v86, v0
	v_mov_b32_e32 v87, v0
	v_mov_b32_e32 v96, v0
	v_mov_b32_e32 v97, v0
	v_mov_b32_e32 v98, v0
	v_mov_b32_e32 v99, v0
	v_mov_b32_e32 v100, v0
	v_mov_b32_e32 v101, v0
	v_mov_b32_e32 v102, v0
	v_mov_b32_e32 v103, v0
	v_mov_b32_e32 v112, v0
	v_mov_b32_e32 v113, v0
	v_mov_b32_e32 v114, v0
	v_mov_b32_e32 v115, v0
	v_mov_b32_e32 v116, v0
	v_mov_b32_e32 v117, v0
	v_mov_b32_e32 v118, v0
	v_mov_b32_e32 v119, v0
	v_mov_b32_e32 v72, v0
	v_mov_b32_e32 v73, v0
	v_mov_b32_e32 v74, v0
	v_mov_b32_e32 v75, v0
	v_mov_b32_e32 v76, v0
	v_mov_b32_e32 v77, v0
	v_mov_b32_e32 v78, v0
	v_mov_b32_e32 v79, v0
	v_mov_b32_e32 v88, v0
	v_mov_b32_e32 v89, v0
	v_mov_b32_e32 v90, v0
	v_mov_b32_e32 v91, v0
	v_mov_b32_e32 v92, v0
	v_mov_b32_e32 v93, v0
	v_mov_b32_e32 v94, v0
	v_mov_b32_e32 v95, v0
	v_mov_b32_e32 v104, v0
	v_mov_b32_e32 v105, v0
	v_mov_b32_e32 v106, v0
	v_mov_b32_e32 v107, v0
	v_mov_b32_e32 v108, v0
	v_mov_b32_e32 v109, v0
	v_mov_b32_e32 v110, v0
	v_mov_b32_e32 v111, v0
	v_mov_b32_e32 v120, v0
	v_mov_b32_e32 v121, v0
	v_mov_b32_e32 v122, v0
	v_mov_b32_e32 v123, v0
	v_mov_b32_e32 v124, v0
	v_mov_b32_e32 v125, v0
	v_mov_b32_e32 v126, v0
	v_mov_b32_e32 v127, v0
	s_cmp_lg_u64 s[16:17], 0
	s_cbranch_scc0 .Lsp_166
	s_setprio 1

; #define PG8_BAR __builtin_amdgcn_s_barrier()
; template <class Epi, class Sched>
; __device__ __forceinline__ void gemm_phase(LAS unsigned char* lds, const GemmP g, const Sched& S, const Epi& E, int tid) {
;     ...
; #pragma unroll
;         for (int a = 0; a < 2; ++a)
; #pragma unroll
;             for (int b = 0; b < 2; ++b)
; #pragma unroll
;                 for (int m = 0; m < 4; ++m)
; #pragma unroll
;                     for (int n = 0; n < 2; ++n) acc[a][b][m][n] = (f32x4){0.f, 0.f, 0.f, 0.f};
;         cur = nxt; cA = nA; cB = nB; ++ui;
;         if (wr == 1) PG8_BAR;
.LBB0_222:
	s_add_u32 s69, s40, 0x100
	s_addc_u32 s70, s41, 0
	s_add_u32 s38, s38, 0x40080
	v_mov_b32_e32 v0, 0
	s_addc_u32 s39, s39, 0
	s_mov_b32 s71, -2
	v_mov_b32_e32 v1, v0
	v_mov_b32_e32 v2, v0
	v_mov_b32_e32 v3, v0
	v_mov_b32_e32 v4, v0
	v_mov_b32_e32 v5, v0
	v_mov_b32_e32 v6, v0
	v_mov_b32_e32 v7, v0
	v_mov_b32_e32 v8, v0
	v_mov_b32_e32 v9, v0
	v_mov_b32_e32 v10, v0
	v_mov_b32_e32 v11, v0
	v_mov_b32_e32 v12, v0
	v_mov_b32_e32 v13, v0
	v_mov_b32_e32 v14, v0
	v_mov_b32_e32 v15, v0
	v_mov_b32_e32 v24, v0
	v_mov_b32_e32 v25, v0
	v_mov_b32_e32 v26, v0
	v_mov_b32_e32 v27, v0
	v_mov_b32_e32 v28, v0
	v_mov_b32_e32 v29, v0
	v_mov_b32_e32 v30, v0
	v_mov_b32_e32 v31, v0
	v_mov_b32_e32 v40, v0
	v_mov_b32_e32 v41, v0
	v_mov_b32_e32 v42, v0
	v_mov_b32_e32 v43, v0
	v_mov_b32_e32 v44, v0
	v_mov_b32_e32 v45, v0
	v_mov_b32_e32 v46, v0
	v_mov_b32_e32 v47, v0
	v_mov_b32_e32 v16, v0
	v_mov_b32_e32 v17, v0
	v_mov_b32_e32 v18, v0
	v_mov_b32_e32 v19, v0
	v_mov_b32_e32 v20, v0
	v_mov_b32_e32 v21, v0
	v_mov_b32_e32 v22, v0
	v_mov_b32_e32 v23, v0
	v_mov_b32_e32 v32, v0
	v_mov_b32_e32 v33, v0
	v_mov_b32_e32 v34, v0
	v_mov_b32_e32 v35, v0
	v_mov_b32_e32 v36, v0
	v_mov_b32_e32 v37, v0
	v_mov_b32_e32 v38, v0
	v_mov_b32_e32 v39, v0
	v_mov_b32_e32 v48, v0
	v_mov_b32_e32 v49, v0
	v_mov_b32_e32 v50, v0
	v_mov_b32_e32 v51, v0
	v_mov_b32_e32 v52, v0
	v_mov_b32_e32 v53, v0
	v_mov_b32_e32 v54, v0
	v_mov_b32_e32 v55, v0
	v_mov_b32_e32 v56, v0
	v_mov_b32_e32 v57, v0
	v_mov_b32_e32 v58, v0
	v_mov_b32_e32 v59, v0
	v_mov_b32_e32 v60, v0
	v_mov_b32_e32 v61, v0
	v_mov_b32_e32 v62, v0
	v_mov_b32_e32 v63, v0
	v_mov_b32_e32 v64, v0
	v_mov_b32_e32 v65, v0
	v_mov_b32_e32 v66, v0
	v_mov_b32_e32 v67, v0
	v_mov_b32_e32 v68, v0
	v_mov_b32_e32 v69, v0
	v_mov_b32_e32 v70, v0
	v_mov_b32_e32 v71, v0
	v_mov_b32_e32 v72, v0
	v_mov_b32_e32 v73, v0
	v_mov_b32_e32 v74, v0
	v_mov_b32_e32 v75, v0
	v_mov_b32_e32 v76, v0
	v_mov_b32_e32 v77, v0
	v_mov_b32_e32 v78, v0
	v_mov_b32_e32 v79, v0
	v_mov_b32_e32 v88, v0
	v_mov_b32_e32 v89, v0
	v_mov_b32_e32 v90, v0
	v_mov_b32_e32 v91, v0
	v_mov_b32_e32 v92, v0
	v_mov_b32_e32 v93, v0
	v_mov_b32_e32 v94, v0
	v_mov_b32_e32 v95, v0
	v_mov_b32_e32 v104, v0
	v_mov_b32_e32 v105, v0
	v_mov_b32_e32 v106, v0
	v_mov_b32_e32 v107, v0
	v_mov_b32_e32 v108, v0
	v_mov_b32_e32 v109, v0
	v_mov_b32_e32 v110, v0
	v_mov_b32_e32 v111, v0
	v_mov_b32_e32 v80, v0
	v_mov_b32_e32 v81, v0
	v_mov_b32_e32 v82, v0
	v_mov_b32_e32 v83, v0
	v_mov_b32_e32 v84, v0
	v_mov_b32_e32 v85, v0
	v_mov_b32_e32 v86, v0
	v_mov_b32_e32 v87, v0
	v_mov_b32_e32 v96, v0
	v_mov_b32_e32 v97, v0
	v_mov_b32_e32 v98, v0
	v_mov_b32_e32 v99, v0
	v_mov_b32_e32 v100, v0
	v_mov_b32_e32 v101, v0
	v_mov_b32_e32 v102, v0
	v_mov_b32_e32 v103, v0
	v_mov_b32_e32 v112, v0
	v_mov_b32_e32 v113, v0
	v_mov_b32_e32 v114, v0
	v_mov_b32_e32 v115, v0
	v_mov_b32_e32 v116, v0
	v_mov_b32_e32 v117, v0
	v_mov_b32_e32 v118, v0
	v_mov_b32_e32 v119, v0
	v_mov_b32_e32 v120, v0
	v_mov_b32_e32 v121, v0
	v_mov_b32_e32 v122, v0
	v_mov_b32_e32 v123, v0
	v_mov_b32_e32 v124, v0
	v_mov_b32_e32 v125, v0
	v_mov_b32_e32 v126, v0
	v_mov_b32_e32 v127, v0
	s_cmp_lg_u64 s[14:15], 0
	s_cbranch_scc0 .Lsp_223
	s_setprio 1

; #define PG8_BAR __builtin_amdgcn_s_barrier()
; template <class Epi, class Sched>
; __device__ __forceinline__ void gemm_phase(LAS unsigned char* lds, const GemmP g, const Sched& S, const Epi& E, int tid) {
;     ...
; #pragma unroll
;         for (int a = 0; a < 2; ++a)
; #pragma unroll
;             for (int b = 0; b < 2; ++b)
; #pragma unroll
;                 for (int m = 0; m < 4; ++m)
; #pragma unroll
;                     for (int n = 0; n < 2; ++n) acc[a][b][m][n] = (f32x4){0.f, 0.f, 0.f, 0.f};
;         cur = nxt; cA = nA; cB = nB; ++ui;
;         if (wr == 1) PG8_BAR;
.LBB0_242:
	s_add_u32 s62, s38, 0x100
	s_addc_u32 s63, s39, 0
	s_add_u32 s36, s36, 0x40080
	v_mov_b32_e32 v0, 0
	s_addc_u32 s37, s37, 0
	s_mov_b32 s64, -2
	v_mov_b32_e32 v1, v0
	v_mov_b32_e32 v2, v0
	v_mov_b32_e32 v3, v0
	v_mov_b32_e32 v4, v0
	v_mov_b32_e32 v5, v0
	v_mov_b32_e32 v6, v0
	v_mov_b32_e32 v7, v0
	v_mov_b32_e32 v8, v0
	v_mov_b32_e32 v9, v0
	v_mov_b32_e32 v10, v0
	v_mov_b32_e32 v11, v0
	v_mov_b32_e32 v12, v0
	v_mov_b32_e32 v13, v0
	v_mov_b32_e32 v14, v0
	v_mov_b32_e32 v15, v0
	v_mov_b32_e32 v24, v0
	v_mov_b32_e32 v25, v0
	v_mov_b32_e32 v26, v0
	v_mov_b32_e32 v27, v0
	v_mov_b32_e32 v28, v0
	v_mov_b32_e32 v29, v0
	v_mov_b32_e32 v30, v0
	v_mov_b32_e32 v31, v0
	v_mov_b32_e32 v40, v0
	v_mov_b32_e32 v41, v0
	v_mov_b32_e32 v42, v0
	v_mov_b32_e32 v43, v0
	v_mov_b32_e32 v44, v0
	v_mov_b32_e32 v45, v0
	v_mov_b32_e32 v46, v0
	v_mov_b32_e32 v47, v0
	v_mov_b32_e32 v16, v0
	v_mov_b32_e32 v17, v0
	v_mov_b32_e32 v18, v0
	v_mov_b32_e32 v19, v0
	v_mov_b32_e32 v20, v0
	v_mov_b32_e32 v21, v0
	v_mov_b32_e32 v22, v0
	v_mov_b32_e32 v23, v0
	v_mov_b32_e32 v32, v0
	v_mov_b32_e32 v33, v0
	v_mov_b32_e32 v34, v0
	v_mov_b32_e32 v35, v0
	v_mov_b32_e32 v36, v0
	v_mov_b32_e32 v37, v0
	v_mov_b32_e32 v38, v0
	v_mov_b32_e32 v39, v0
	v_mov_b32_e32 v48, v0
	v_mov_b32_e32 v49, v0
	v_mov_b32_e32 v50, v0
	v_mov_b32_e32 v51, v0
	v_mov_b32_e32 v52, v0
	v_mov_b32_e32 v53, v0
	v_mov_b32_e32 v54, v0
	v_mov_b32_e32 v55, v0
	v_mov_b32_e32 v56, v0
	v_mov_b32_e32 v57, v0
	v_mov_b32_e32 v58, v0
	v_mov_b32_e32 v59, v0
	v_mov_b32_e32 v60, v0
	v_mov_b32_e32 v61, v0
	v_mov_b32_e32 v62, v0
	v_mov_b32_e32 v63, v0
	v_mov_b32_e32 v64, v0
	v_mov_b32_e32 v65, v0
	v_mov_b32_e32 v66, v0
	v_mov_b32_e32 v67, v0
	v_mov_b32_e32 v68, v0
	v_mov_b32_e32 v69, v0
	v_mov_b32_e32 v70, v0
	v_mov_b32_e32 v71, v0
	v_mov_b32_e32 v72, v0
	v_mov_b32_e32 v73, v0
	v_mov_b32_e32 v74, v0
	v_mov_b32_e32 v75, v0
	v_mov_b32_e32 v76, v0
	v_mov_b32_e32 v77, v0
	v_mov_b32_e32 v78, v0
	v_mov_b32_e32 v79, v0
	v_mov_b32_e32 v88, v0
	v_mov_b32_e32 v89, v0
	v_mov_b32_e32 v90, v0
	v_mov_b32_e32 v91, v0
	v_mov_b32_e32 v92, v0
	v_mov_b32_e32 v93, v0
	v_mov_b32_e32 v94, v0
	v_mov_b32_e32 v95, v0
	v_mov_b32_e32 v104, v0
	v_mov_b32_e32 v105, v0
	v_mov_b32_e32 v106, v0
	v_mov_b32_e32 v107, v0
	v_mov_b32_e32 v108, v0
	v_mov_b32_e32 v109, v0
	v_mov_b32_e32 v110, v0
	v_mov_b32_e32 v111, v0
	v_mov_b32_e32 v80, v0
	v_mov_b32_e32 v81, v0
	v_mov_b32_e32 v82, v0
	v_mov_b32_e32 v83, v0
	v_mov_b32_e32 v84, v0
	v_mov_b32_e32 v85, v0
	v_mov_b32_e32 v86, v0
	v_mov_b32_e32 v87, v0
	v_mov_b32_e32 v96, v0
	v_mov_b32_e32 v97, v0
	v_mov_b32_e32 v98, v0
	v_mov_b32_e32 v99, v0
	v_mov_b32_e32 v100, v0
	v_mov_b32_e32 v101, v0
	v_mov_b32_e32 v102, v0
	v_mov_b32_e32 v103, v0
	v_mov_b32_e32 v112, v0
	v_mov_b32_e32 v113, v0
	v_mov_b32_e32 v114, v0
	v_mov_b32_e32 v115, v0
	v_mov_b32_e32 v116, v0
	v_mov_b32_e32 v117, v0
	v_mov_b32_e32 v118, v0
	v_mov_b32_e32 v119, v0
	v_mov_b32_e32 v120, v0
	v_mov_b32_e32 v121, v0
	v_mov_b32_e32 v122, v0
	v_mov_b32_e32 v123, v0
	v_mov_b32_e32 v124, v0
	v_mov_b32_e32 v125, v0
	v_mov_b32_e32 v126, v0
	v_mov_b32_e32 v127, v0
	s_cmp_lg_u64 s[12:13], 0
	s_cbranch_scc0 .Lsp_243
	s_setprio 1

; #define PG8_BAR __builtin_amdgcn_s_barrier()
; template <class Epi, class Sched>
; __device__ __forceinline__ void gemm_phase(LAS unsigned char* lds, const GemmP g, const Sched& S, const Epi& E, int tid) {
;     ...
; #pragma unroll
;         for (int a = 0; a < 2; ++a)
; #pragma unroll
;             for (int b = 0; b < 2; ++b)
; #pragma unroll
;                 for (int m = 0; m < 4; ++m)
; #pragma unroll
;                     for (int n = 0; n < 2; ++n) acc[a][b][m][n] = (f32x4){0.f, 0.f, 0.f, 0.f};
;         cur = nxt; cA = nA; cB = nB; ++ui;
;         if (wr == 1) PG8_BAR;
.LBB0_444:
	s_add_u32 s12, s6, 0x100
	s_addc_u32 s13, s7, 0
	s_add_u32 s4, s4, 0x40080
	v_mov_b32_e32 v0, 0
	s_addc_u32 s5, s5, 0
	s_mov_b32 s14, -2
	s_waitcnt lgkmcnt(0)
	v_mov_b32_e32 v1, v0
	v_mov_b32_e32 v2, v0
	v_mov_b32_e32 v3, v0
	v_mov_b32_e32 v4, v0
	v_mov_b32_e32 v5, v0
	v_mov_b32_e32 v6, v0
	v_mov_b32_e32 v7, v0
	v_mov_b32_e32 v8, v0
	v_mov_b32_e32 v9, v0
	v_mov_b32_e32 v10, v0
	v_mov_b32_e32 v11, v0
	v_mov_b32_e32 v12, v0
	v_mov_b32_e32 v13, v0
	v_mov_b32_e32 v14, v0
	v_mov_b32_e32 v15, v0
	v_mov_b32_e32 v16, v0
	v_mov_b32_e32 v17, v0
	v_mov_b32_e32 v18, v0
	v_mov_b32_e32 v19, v0
	v_mov_b32_e32 v20, v0
	v_mov_b32_e32 v21, v0
	v_mov_b32_e32 v22, v0
	v_mov_b32_e32 v23, v0
	v_mov_b32_e32 v24, v0
	v_mov_b32_e32 v25, v0
	v_mov_b32_e32 v26, v0
	v_mov_b32_e32 v27, v0
	v_mov_b32_e32 v28, v0
	v_mov_b32_e32 v29, v0
	v_mov_b32_e32 v30, v0
	v_mov_b32_e32 v31, v0
	v_mov_b32_e32 v56, v0
	v_mov_b32_e32 v57, v0
	v_mov_b32_e32 v58, v0
	v_mov_b32_e32 v59, v0
	v_mov_b32_e32 v64, v0
	v_mov_b32_e32 v65, v0
	v_mov_b32_e32 v66, v0
	v_mov_b32_e32 v67, v0
	v_mov_b32_e32 v72, v0
	v_mov_b32_e32 v73, v0
	v_mov_b32_e32 v74, v0
	v_mov_b32_e32 v75, v0
	v_mov_b32_e32 v76, v0
	v_mov_b32_e32 v77, v0
	v_mov_b32_e32 v78, v0
	v_mov_b32_e32 v79, v0
	v_mov_b32_e32 v80, v0
	v_mov_b32_e32 v81, v0
	v_mov_b32_e32 v82, v0
	v_mov_b32_e32 v83, v0
	v_mov_b32_e32 v84, v0
	v_mov_b32_e32 v85, v0
	v_mov_b32_e32 v86, v0
	v_mov_b32_e32 v87, v0
	v_mov_b32_e32 v88, v0
	v_mov_b32_e32 v89, v0
	v_mov_b32_e32 v90, v0
	v_mov_b32_e32 v91, v0
	v_mov_b32_e32 v92, v0
	v_mov_b32_e32 v93, v0
	v_mov_b32_e32 v94, v0
	v_mov_b32_e32 v95, v0
	v_mov_b32_e32 v32, v0
	v_mov_b32_e32 v33, v0
	v_mov_b32_e32 v34, v0
	v_mov_b32_e32 v35, v0
	v_mov_b32_e32 v36, v0
	v_mov_b32_e32 v37, v0
	v_mov_b32_e32 v38, v0
	v_mov_b32_e32 v39, v0
	v_mov_b32_e32 v40, v0
	v_mov_b32_e32 v41, v0
	v_mov_b32_e32 v42, v0
	v_mov_b32_e32 v43, v0
	v_mov_b32_e32 v44, v0
	v_mov_b32_e32 v45, v0
	v_mov_b32_e32 v46, v0
	v_mov_b32_e32 v47, v0
	v_mov_b32_e32 v48, v0
	v_mov_b32_e32 v49, v0
	v_mov_b32_e32 v50, v0
	v_mov_b32_e32 v51, v0
	v_mov_b32_e32 v52, v0
	v_mov_b32_e32 v53, v0
	v_mov_b32_e32 v54, v0
	v_mov_b32_e32 v55, v0
	v_mov_b32_e32 v60, v0
	v_mov_b32_e32 v61, v0
	v_mov_b32_e32 v62, v0
	v_mov_b32_e32 v63, v0
	v_mov_b32_e32 v68, v0
	v_mov_b32_e32 v69, v0
	v_mov_b32_e32 v70, v0
	v_mov_b32_e32 v71, v0
	v_mov_b32_e32 v96, v0
	v_mov_b32_e32 v97, v0
	v_mov_b32_e32 v98, v0
	v_mov_b32_e32 v99, v0
	v_mov_b32_e32 v100, v0
	v_mov_b32_e32 v101, v0
	v_mov_b32_e32 v102, v0
	v_mov_b32_e32 v103, v0
	v_mov_b32_e32 v104, v0
	v_mov_b32_e32 v105, v0
	v_mov_b32_e32 v106, v0
	v_mov_b32_e32 v107, v0
	v_mov_b32_e32 v108, v0
	v_mov_b32_e32 v109, v0
	v_mov_b32_e32 v110, v0
	v_mov_b32_e32 v111, v0
	v_mov_b32_e32 v112, v0
	v_mov_b32_e32 v113, v0
	v_mov_b32_e32 v114, v0
	v_mov_b32_e32 v115, v0
	v_mov_b32_e32 v116, v0
	v_mov_b32_e32 v117, v0
	v_mov_b32_e32 v118, v0
	v_mov_b32_e32 v119, v0
	v_mov_b32_e32 v120, v0
	v_mov_b32_e32 v121, v0
	v_mov_b32_e32 v122, v0
	v_mov_b32_e32 v123, v0
	v_mov_b32_e32 v124, v0
	v_mov_b32_e32 v125, v0
	v_mov_b32_e32 v126, v0
	v_mov_b32_e32 v127, v0
	s_cmp_lg_u64 s[48:49], 0
	s_cbranch_scc0 .Lsp_445
	s_setprio 1

; #define PG8_BAR __builtin_amdgcn_s_barrier()
; template <class Epi, class Sched>
; __device__ __forceinline__ void gemm_phase(LAS unsigned char* lds, const GemmP g, const Sched& S, const Epi& E, int tid) {
;     ...
; #pragma unroll
;         for (int a = 0; a < 2; ++a)
; #pragma unroll
;             for (int b = 0; b < 2; ++b)
; #pragma unroll
;                 for (int m = 0; m < 4; ++m)
; #pragma unroll
;                     for (int n = 0; n < 2; ++n) acc[a][b][m][n] = (f32x4){0.f, 0.f, 0.f, 0.f};
;         cur = nxt; cA = nA; cB = nB; ++ui;
;         if (wr == 1) PG8_BAR;
.LBB0_995:
	s_add_u32 s5, s28, 0x100
	s_addc_u32 s56, s29, 0
	s_add_u32 s26, s26, 0x40080
	v_mov_b32_e32 v0, 0
	s_addc_u32 s27, s27, 0
	s_mov_b32 s57, -2
	v_mov_b32_e32 v1, v0
	v_mov_b32_e32 v2, v0
	v_mov_b32_e32 v3, v0
	v_mov_b32_e32 v4, v0
	v_mov_b32_e32 v5, v0
	v_mov_b32_e32 v6, v0
	v_mov_b32_e32 v7, v0
	v_mov_b32_e32 v16, v0
	v_mov_b32_e32 v17, v0
	v_mov_b32_e32 v18, v0
	v_mov_b32_e32 v19, v0
	v_mov_b32_e32 v20, v0
	v_mov_b32_e32 v21, v0
	v_mov_b32_e32 v22, v0
	v_mov_b32_e32 v23, v0
	v_mov_b32_e32 v32, v0
	v_mov_b32_e32 v33, v0
	v_mov_b32_e32 v34, v0
	v_mov_b32_e32 v35, v0
	v_mov_b32_e32 v36, v0
	v_mov_b32_e32 v37, v0
	v_mov_b32_e32 v38, v0
	v_mov_b32_e32 v39, v0
	v_mov_b32_e32 v48, v0
	v_mov_b32_e32 v49, v0
	v_mov_b32_e32 v50, v0
	v_mov_b32_e32 v51, v0
	v_mov_b32_e32 v52, v0
	v_mov_b32_e32 v53, v0
	v_mov_b32_e32 v54, v0
	v_mov_b32_e32 v55, v0
	v_mov_b32_e32 v8, v0
	v_mov_b32_e32 v9, v0
	v_mov_b32_e32 v10, v0
	v_mov_b32_e32 v11, v0
	v_mov_b32_e32 v12, v0
	v_mov_b32_e32 v13, v0
	v_mov_b32_e32 v14, v0
	v_mov_b32_e32 v15, v0
	v_mov_b32_e32 v24, v0
	v_mov_b32_e32 v25, v0
	v_mov_b32_e32 v26, v0
	v_mov_b32_e32 v27, v0
	v_mov_b32_e32 v28, v0
	v_mov_b32_e32 v29, v0
	v_mov_b32_e32 v30, v0
	v_mov_b32_e32 v31, v0
	v_mov_b32_e32 v40, v0
	v_mov_b32_e32 v41, v0
	v_mov_b32_e32 v42, v0
	v_mov_b32_e32 v43, v0
	v_mov_b32_e32 v44, v0
	v_mov_b32_e32 v45, v0
	v_mov_b32_e32 v46, v0
	v_mov_b32_e32 v47, v0
	v_mov_b32_e32 v56, v0
	v_mov_b32_e32 v57, v0
	v_mov_b32_e32 v58, v0
	v_mov_b32_e32 v59, v0
	v_mov_b32_e32 v60, v0
	v_mov_b32_e32 v61, v0
	v_mov_b32_e32 v62, v0
	v_mov_b32_e32 v63, v0
	v_mov_b32_e32 v64, v0
	v_mov_b32_e32 v65, v0
	v_mov_b32_e32 v66, v0
	v_mov_b32_e32 v67, v0
	v_mov_b32_e32 v68, v0
	v_mov_b32_e32 v69, v0
	v_mov_b32_e32 v70, v0
	v_mov_b32_e32 v71, v0
	v_mov_b32_e32 v80, v0
	v_mov_b32_e32 v81, v0
	v_mov_b32_e32 v82, v0
	v_mov_b32_e32 v83, v0
	v_mov_b32_e32 v84, v0
	v_mov_b32_e32 v85, v0
	v_mov_b32_e32 v86, v0
	v_mov_b32_e32 v87, v0
	v_mov_b32_e32 v96, v0
	v_mov_b32_e32 v97, v0
	v_mov_b32_e32 v98, v0
	v_mov_b32_e32 v99, v0
	v_mov_b32_e32 v100, v0
	v_mov_b32_e32 v101, v0
	v_mov_b32_e32 v102, v0
	v_mov_b32_e32 v103, v0
	v_mov_b32_e32 v112, v0
	v_mov_b32_e32 v113, v0
	v_mov_b32_e32 v114, v0
	v_mov_b32_e32 v115, v0
	v_mov_b32_e32 v116, v0
	v_mov_b32_e32 v117, v0
	v_mov_b32_e32 v118, v0
	v_mov_b32_e32 v119, v0
	v_mov_b32_e32 v72, v0
	v_mov_b32_e32 v73, v0
	v_mov_b32_e32 v74, v0
	v_mov_b32_e32 v75, v0
	v_mov_b32_e32 v76, v0
	v_mov_b32_e32 v77, v0
	v_mov_b32_e32 v78, v0
	v_mov_b32_e32 v79, v0
	v_mov_b32_e32 v88, v0
	v_mov_b32_e32 v89, v0
	v_mov_b32_e32 v90, v0
	v_mov_b32_e32 v91, v0
	v_mov_b32_e32 v92, v0
	v_mov_b32_e32 v93, v0
	v_mov_b32_e32 v94, v0
	v_mov_b32_e32 v95, v0
	v_mov_b32_e32 v104, v0
	v_mov_b32_e32 v105, v0
	v_mov_b32_e32 v106, v0
	v_mov_b32_e32 v107, v0
	v_mov_b32_e32 v108, v0
	v_mov_b32_e32 v109, v0
	v_mov_b32_e32 v110, v0
	v_mov_b32_e32 v111, v0
	v_mov_b32_e32 v120, v0
	v_mov_b32_e32 v121, v0
	v_mov_b32_e32 v122, v0
	v_mov_b32_e32 v123, v0
	v_mov_b32_e32 v124, v0
	v_mov_b32_e32 v125, v0
	v_mov_b32_e32 v126, v0
	v_mov_b32_e32 v127, v0
	s_sub_i32 s32, s44, s4
	s_bfe_u32 s98, s32, 0x10006
	s_bfe_u32 s32, s32, 0x10007
	s_cmp_lg_u64 s[10:11], 0
	s_cselect_b32 s99, 1, 0
	s_xor_b32 s98, s98, s99
	s_or_b32 s99, s98, s32
	s_xor_b32 s32, s32, 1
	s_or_b32 s98, s98, s32
	s_cmp_eq_u32 s43, 0x7fffffff
	s_cselect_b32 s32, 0, s99
	s_cselect_b32 s98, 0, s98
	s_and_b32 s99, s32, s98
	s_cmp_lg_u64 s[16:17], 0
	s_cbranch_scc0 .Lsp_996
	s_setprio 1

; #define PG8_BAR __builtin_amdgcn_s_barrier()
; template <class Epi, class Sched>
; __device__ __forceinline__ void gemm_phase(LAS unsigned char* lds, const GemmP g, const Sched& S, const Epi& E, int tid) {
;     ...
; #pragma unroll
;         for (int a = 0; a < 2; ++a)
; #pragma unroll
;             for (int b = 0; b < 2; ++b)
; #pragma unroll
;                 for (int m = 0; m < 4; ++m)
; #pragma unroll
;                     for (int n = 0; n < 2; ++n) acc[a][b][m][n] = (f32x4){0.f, 0.f, 0.f, 0.f};
;         cur = nxt; cA = nA; cB = nB; ++ui;
;         if (wr == 1) PG8_BAR;
.LBB0_1052:
	s_add_u32 s52, s22, 0x100
	s_addc_u32 s53, s23, 0
	s_add_u32 s20, s20, 0x40080
	v_mov_b32_e32 v0, 0
	s_addc_u32 s21, s21, 0
	s_mov_b32 s54, -2
	v_mov_b32_e32 v1, v0
	v_mov_b32_e32 v2, v0
	v_mov_b32_e32 v3, v0
	v_mov_b32_e32 v4, v0
	v_mov_b32_e32 v5, v0
	v_mov_b32_e32 v6, v0
	v_mov_b32_e32 v7, v0
	v_mov_b32_e32 v8, v0
	v_mov_b32_e32 v9, v0
	v_mov_b32_e32 v10, v0
	v_mov_b32_e32 v11, v0
	v_mov_b32_e32 v12, v0
	v_mov_b32_e32 v13, v0
	v_mov_b32_e32 v14, v0
	v_mov_b32_e32 v15, v0
	v_mov_b32_e32 v24, v0
	v_mov_b32_e32 v25, v0
	v_mov_b32_e32 v26, v0
	v_mov_b32_e32 v27, v0
	v_mov_b32_e32 v28, v0
	v_mov_b32_e32 v29, v0
	v_mov_b32_e32 v30, v0
	v_mov_b32_e32 v31, v0
	v_mov_b32_e32 v40, v0
	v_mov_b32_e32 v41, v0
	v_mov_b32_e32 v42, v0
	v_mov_b32_e32 v43, v0
	v_mov_b32_e32 v44, v0
	v_mov_b32_e32 v45, v0
	v_mov_b32_e32 v46, v0
	v_mov_b32_e32 v47, v0
	v_mov_b32_e32 v16, v0
	v_mov_b32_e32 v17, v0
	v_mov_b32_e32 v18, v0
	v_mov_b32_e32 v19, v0
	v_mov_b32_e32 v20, v0
	v_mov_b32_e32 v21, v0
	v_mov_b32_e32 v22, v0
	v_mov_b32_e32 v23, v0
	v_mov_b32_e32 v32, v0
	v_mov_b32_e32 v33, v0
	v_mov_b32_e32 v34, v0
	v_mov_b32_e32 v35, v0
	v_mov_b32_e32 v36, v0
	v_mov_b32_e32 v37, v0
	v_mov_b32_e32 v38, v0
	v_mov_b32_e32 v39, v0
	v_mov_b32_e32 v48, v0
	v_mov_b32_e32 v49, v0
	v_mov_b32_e32 v50, v0
	v_mov_b32_e32 v51, v0
	v_mov_b32_e32 v52, v0
	v_mov_b32_e32 v53, v0
	v_mov_b32_e32 v54, v0
	v_mov_b32_e32 v55, v0
	v_mov_b32_e32 v56, v0
	v_mov_b32_e32 v57, v0
	v_mov_b32_e32 v58, v0
	v_mov_b32_e32 v59, v0
	v_mov_b32_e32 v60, v0
	v_mov_b32_e32 v61, v0
	v_mov_b32_e32 v62, v0
	v_mov_b32_e32 v63, v0
	v_mov_b32_e32 v64, v0
	v_mov_b32_e32 v65, v0
	v_mov_b32_e32 v66, v0
	v_mov_b32_e32 v67, v0
	v_mov_b32_e32 v68, v0
	v_mov_b32_e32 v69, v0
	v_mov_b32_e32 v70, v0
	v_mov_b32_e32 v71, v0
	v_mov_b32_e32 v72, v0
	v_mov_b32_e32 v73, v0
	v_mov_b32_e32 v74, v0
	v_mov_b32_e32 v75, v0
	v_mov_b32_e32 v76, v0
	v_mov_b32_e32 v77, v0
	v_mov_b32_e32 v78, v0
	v_mov_b32_e32 v79, v0
	v_mov_b32_e32 v88, v0
	v_mov_b32_e32 v89, v0
	v_mov_b32_e32 v90, v0
	v_mov_b32_e32 v91, v0
	v_mov_b32_e32 v92, v0
	v_mov_b32_e32 v93, v0
	v_mov_b32_e32 v94, v0
	v_mov_b32_e32 v95, v0
	v_mov_b32_e32 v104, v0
	v_mov_b32_e32 v105, v0
	v_mov_b32_e32 v106, v0
	v_mov_b32_e32 v107, v0
	v_mov_b32_e32 v108, v0
	v_mov_b32_e32 v109, v0
	v_mov_b32_e32 v110, v0
	v_mov_b32_e32 v111, v0
	v_mov_b32_e32 v80, v0
	v_mov_b32_e32 v81, v0
	v_mov_b32_e32 v82, v0
	v_mov_b32_e32 v83, v0
	v_mov_b32_e32 v84, v0
	v_mov_b32_e32 v85, v0
	v_mov_b32_e32 v86, v0
	v_mov_b32_e32 v87, v0
	v_mov_b32_e32 v96, v0
	v_mov_b32_e32 v97, v0
	v_mov_b32_e32 v98, v0
	v_mov_b32_e32 v99, v0
	v_mov_b32_e32 v100, v0
	v_mov_b32_e32 v101, v0
	v_mov_b32_e32 v102, v0
	v_mov_b32_e32 v103, v0
	v_mov_b32_e32 v112, v0
	v_mov_b32_e32 v113, v0
	v_mov_b32_e32 v114, v0
	v_mov_b32_e32 v115, v0
	v_mov_b32_e32 v116, v0
	v_mov_b32_e32 v117, v0
	v_mov_b32_e32 v118, v0
	v_mov_b32_e32 v119, v0
	v_mov_b32_e32 v120, v0
	v_mov_b32_e32 v121, v0
	v_mov_b32_e32 v122, v0
	v_mov_b32_e32 v123, v0
	v_mov_b32_e32 v124, v0
	v_mov_b32_e32 v125, v0
	v_mov_b32_e32 v126, v0
	v_mov_b32_e32 v127, v0
	s_cmp_lg_u64 s[12:13], 0
	s_cbranch_scc0 .Lsp_1053
	s_setprio 1

; #define PG8_BAR __builtin_amdgcn_s_barrier()
; template <class Epi, class Sched>
; __device__ __forceinline__ void gemm_phase(LAS unsigned char* lds, const GemmP g, const Sched& S, const Epi& E, int tid) {
;     ...
; #pragma unroll
;         for (int a = 0; a < 2; ++a)
; #pragma unroll
;             for (int b = 0; b < 2; ++b)
; #pragma unroll
;                 for (int m = 0; m < 4; ++m)
; #pragma unroll
;                     for (int n = 0; n < 2; ++n) acc[a][b][m][n] = (f32x4){0.f, 0.f, 0.f, 0.f};
;         cur = nxt; cA = nA; cB = nB; ++ui;
;         if (wr == 1) PG8_BAR;
.LBB0_1072:
	s_add_u32 s45, s18, 0x100
	s_addc_u32 s46, s19, 0
	s_add_u32 s16, s16, 0x40080
	v_mov_b32_e32 v0, 0
	s_addc_u32 s17, s17, 0
	s_mov_b32 s47, -2
	v_mov_b32_e32 v1, v0
	v_mov_b32_e32 v2, v0
	v_mov_b32_e32 v3, v0
	v_mov_b32_e32 v4, v0
	v_mov_b32_e32 v5, v0
	v_mov_b32_e32 v6, v0
	v_mov_b32_e32 v7, v0
	v_mov_b32_e32 v8, v0
	v_mov_b32_e32 v9, v0
	v_mov_b32_e32 v10, v0
	v_mov_b32_e32 v11, v0
	v_mov_b32_e32 v12, v0
	v_mov_b32_e32 v13, v0
	v_mov_b32_e32 v14, v0
	v_mov_b32_e32 v15, v0
	v_mov_b32_e32 v24, v0
	v_mov_b32_e32 v25, v0
	v_mov_b32_e32 v26, v0
	v_mov_b32_e32 v27, v0
	v_mov_b32_e32 v28, v0
	v_mov_b32_e32 v29, v0
	v_mov_b32_e32 v30, v0
	v_mov_b32_e32 v31, v0
	v_mov_b32_e32 v40, v0
	v_mov_b32_e32 v41, v0
	v_mov_b32_e32 v42, v0
	v_mov_b32_e32 v43, v0
	v_mov_b32_e32 v44, v0
	v_mov_b32_e32 v45, v0
	v_mov_b32_e32 v46, v0
	v_mov_b32_e32 v47, v0
	v_mov_b32_e32 v16, v0
	v_mov_b32_e32 v17, v0
	v_mov_b32_e32 v18, v0
	v_mov_b32_e32 v19, v0
	v_mov_b32_e32 v20, v0
	v_mov_b32_e32 v21, v0
	v_mov_b32_e32 v22, v0
	v_mov_b32_e32 v23, v0
	v_mov_b32_e32 v32, v0
	v_mov_b32_e32 v33, v0
	v_mov_b32_e32 v34, v0
	v_mov_b32_e32 v35, v0
	v_mov_b32_e32 v36, v0
	v_mov_b32_e32 v37, v0
	v_mov_b32_e32 v38, v0
	v_mov_b32_e32 v39, v0
	v_mov_b32_e32 v48, v0
	v_mov_b32_e32 v49, v0
	v_mov_b32_e32 v50, v0
	v_mov_b32_e32 v51, v0
	v_mov_b32_e32 v52, v0
	v_mov_b32_e32 v53, v0
	v_mov_b32_e32 v54, v0
	v_mov_b32_e32 v55, v0
	v_mov_b32_e32 v56, v0
	v_mov_b32_e32 v57, v0
	v_mov_b32_e32 v58, v0
	v_mov_b32_e32 v59, v0
	v_mov_b32_e32 v60, v0
	v_mov_b32_e32 v61, v0
	v_mov_b32_e32 v62, v0
	v_mov_b32_e32 v63, v0
	v_mov_b32_e32 v64, v0
	v_mov_b32_e32 v65, v0
	v_mov_b32_e32 v66, v0
	v_mov_b32_e32 v67, v0
	v_mov_b32_e32 v68, v0
	v_mov_b32_e32 v69, v0
	v_mov_b32_e32 v70, v0
	v_mov_b32_e32 v71, v0
	v_mov_b32_e32 v72, v0
	v_mov_b32_e32 v73, v0
	v_mov_b32_e32 v74, v0
	v_mov_b32_e32 v75, v0
	v_mov_b32_e32 v76, v0
	v_mov_b32_e32 v77, v0
	v_mov_b32_e32 v78, v0
	v_mov_b32_e32 v79, v0
	v_mov_b32_e32 v88, v0
	v_mov_b32_e32 v89, v0
	v_mov_b32_e32 v90, v0
	v_mov_b32_e32 v91, v0
	v_mov_b32_e32 v92, v0
	v_mov_b32_e32 v93, v0
	v_mov_b32_e32 v94, v0
	v_mov_b32_e32 v95, v0
	v_mov_b32_e32 v104, v0
	v_mov_b32_e32 v105, v0
	v_mov_b32_e32 v106, v0
	v_mov_b32_e32 v107, v0
	v_mov_b32_e32 v108, v0
	v_mov_b32_e32 v109, v0
	v_mov_b32_e32 v110, v0
	v_mov_b32_e32 v111, v0
	v_mov_b32_e32 v80, v0
	v_mov_b32_e32 v81, v0
	v_mov_b32_e32 v82, v0
	v_mov_b32_e32 v83, v0
	v_mov_b32_e32 v84, v0
	v_mov_b32_e32 v85, v0
	v_mov_b32_e32 v86, v0
	v_mov_b32_e32 v87, v0
	v_mov_b32_e32 v96, v0
	v_mov_b32_e32 v97, v0
	v_mov_b32_e32 v98, v0
	v_mov_b32_e32 v99, v0
	v_mov_b32_e32 v100, v0
	v_mov_b32_e32 v101, v0
	v_mov_b32_e32 v102, v0
	v_mov_b32_e32 v103, v0
	v_mov_b32_e32 v112, v0
	v_mov_b32_e32 v113, v0
	v_mov_b32_e32 v114, v0
	v_mov_b32_e32 v115, v0
	v_mov_b32_e32 v116, v0
	v_mov_b32_e32 v117, v0
	v_mov_b32_e32 v118, v0
	v_mov_b32_e32 v119, v0
	v_mov_b32_e32 v120, v0
	v_mov_b32_e32 v121, v0
	v_mov_b32_e32 v122, v0
	v_mov_b32_e32 v123, v0
	v_mov_b32_e32 v124, v0
	v_mov_b32_e32 v125, v0
	v_mov_b32_e32 v126, v0
	v_mov_b32_e32 v127, v0
	s_cmp_lg_u64 s[8:9], 0
	s_cbranch_scc0 .Lsp_1073
	s_setprio 1

; #define PG8_BAR __builtin_amdgcn_s_barrier()
; template <class Epi, class Sched>
; __device__ __forceinline__ void gemm_phase(LAS unsigned char* lds, const GemmP g, const Sched& S, const Epi& E, int tid) {
;     ...
; #pragma unroll
;         for (int a = 0; a < 2; ++a)
; #pragma unroll
;             for (int b = 0; b < 2; ++b)
; #pragma unroll
;                 for (int m = 0; m < 4; ++m)
; #pragma unroll
;                     for (int n = 0; n < 2; ++n) acc[a][b][m][n] = (f32x4){0.f, 0.f, 0.f, 0.f};
;         cur = nxt; cA = nA; cB = nB; ++ui;
;         if (wr == 1) PG8_BAR;
.LBB0_1162:
	s_add_u32 s12, s8, 0x100
	s_addc_u32 s13, s9, 0
	s_add_u32 s6, s6, 0x40080
	v_mov_b32_e32 v0, 0
	s_addc_u32 s7, s7, 0
	s_mov_b32 s14, -2
	s_waitcnt lgkmcnt(0)
	v_mov_b32_e32 v1, v0
	v_mov_b32_e32 v2, v0
	v_mov_b32_e32 v3, v0
	v_mov_b32_e32 v4, v0
	v_mov_b32_e32 v5, v0
	v_mov_b32_e32 v6, v0
	v_mov_b32_e32 v7, v0
	v_mov_b32_e32 v8, v0
	v_mov_b32_e32 v9, v0
	v_mov_b32_e32 v10, v0
	v_mov_b32_e32 v11, v0
	v_mov_b32_e32 v12, v0
	v_mov_b32_e32 v13, v0
	v_mov_b32_e32 v14, v0
	v_mov_b32_e32 v15, v0
	v_mov_b32_e32 v16, v0
	v_mov_b32_e32 v17, v0
	v_mov_b32_e32 v18, v0
	v_mov_b32_e32 v19, v0
	v_mov_b32_e32 v20, v0
	v_mov_b32_e32 v21, v0
	v_mov_b32_e32 v22, v0
	v_mov_b32_e32 v23, v0
	v_mov_b32_e32 v24, v0
	v_mov_b32_e32 v25, v0
	v_mov_b32_e32 v26, v0
	v_mov_b32_e32 v27, v0
	v_mov_b32_e32 v28, v0
	v_mov_b32_e32 v29, v0
	v_mov_b32_e32 v30, v0
	v_mov_b32_e32 v31, v0
	v_mov_b32_e32 v56, v0
	v_mov_b32_e32 v57, v0
	v_mov_b32_e32 v58, v0
	v_mov_b32_e32 v59, v0
	v_mov_b32_e32 v64, v0
	v_mov_b32_e32 v65, v0
	v_mov_b32_e32 v66, v0
	v_mov_b32_e32 v67, v0
	v_mov_b32_e32 v72, v0
	v_mov_b32_e32 v73, v0
	v_mov_b32_e32 v74, v0
	v_mov_b32_e32 v75, v0
	v_mov_b32_e32 v76, v0
	v_mov_b32_e32 v77, v0
	v_mov_b32_e32 v78, v0
	v_mov_b32_e32 v79, v0
	v_mov_b32_e32 v80, v0
	v_mov_b32_e32 v81, v0
	v_mov_b32_e32 v82, v0
	v_mov_b32_e32 v83, v0
	v_mov_b32_e32 v84, v0
	v_mov_b32_e32 v85, v0
	v_mov_b32_e32 v86, v0
	v_mov_b32_e32 v87, v0
	v_mov_b32_e32 v88, v0
	v_mov_b32_e32 v89, v0
	v_mov_b32_e32 v90, v0
	v_mov_b32_e32 v91, v0
	v_mov_b32_e32 v92, v0
	v_mov_b32_e32 v93, v0
	v_mov_b32_e32 v94, v0
	v_mov_b32_e32 v95, v0
	v_mov_b32_e32 v32, v0
	v_mov_b32_e32 v33, v0
	v_mov_b32_e32 v34, v0
	v_mov_b32_e32 v35, v0
	v_mov_b32_e32 v36, v0
	v_mov_b32_e32 v37, v0
	v_mov_b32_e32 v38, v0
	v_mov_b32_e32 v39, v0
	v_mov_b32_e32 v40, v0
	v_mov_b32_e32 v41, v0
	v_mov_b32_e32 v42, v0
	v_mov_b32_e32 v43, v0
	v_mov_b32_e32 v44, v0
	v_mov_b32_e32 v45, v0
	v_mov_b32_e32 v46, v0
	v_mov_b32_e32 v47, v0
	v_mov_b32_e32 v48, v0
	v_mov_b32_e32 v49, v0
	v_mov_b32_e32 v50, v0
	v_mov_b32_e32 v51, v0
	v_mov_b32_e32 v52, v0
	v_mov_b32_e32 v53, v0
	v_mov_b32_e32 v54, v0
	v_mov_b32_e32 v55, v0
	v_mov_b32_e32 v60, v0
	v_mov_b32_e32 v61, v0
	v_mov_b32_e32 v62, v0
	v_mov_b32_e32 v63, v0
	v_mov_b32_e32 v68, v0
	v_mov_b32_e32 v69, v0
	v_mov_b32_e32 v70, v0
	v_mov_b32_e32 v71, v0
	v_mov_b32_e32 v96, v0
	v_mov_b32_e32 v97, v0
	v_mov_b32_e32 v98, v0
	v_mov_b32_e32 v99, v0
	v_mov_b32_e32 v100, v0
	v_mov_b32_e32 v101, v0
	v_mov_b32_e32 v102, v0
	v_mov_b32_e32 v103, v0
	v_mov_b32_e32 v104, v0
	v_mov_b32_e32 v105, v0
	v_mov_b32_e32 v106, v0
	v_mov_b32_e32 v107, v0
	v_mov_b32_e32 v108, v0
	v_mov_b32_e32 v109, v0
	v_mov_b32_e32 v110, v0
	v_mov_b32_e32 v111, v0
	v_mov_b32_e32 v112, v0
	v_mov_b32_e32 v113, v0
	v_mov_b32_e32 v114, v0
	v_mov_b32_e32 v115, v0
	v_mov_b32_e32 v116, v0
	v_mov_b32_e32 v117, v0
	v_mov_b32_e32 v118, v0
	v_mov_b32_e32 v119, v0
	v_mov_b32_e32 v128, v0
	v_mov_b32_e32 v129, v0
	v_mov_b32_e32 v130, v0
	v_mov_b32_e32 v131, v0
	v_mov_b32_e32 v120, v0
	v_mov_b32_e32 v121, v0
	v_mov_b32_e32 v122, v0
	v_mov_b32_e32 v123, v0
	s_sub_i32 s32, s41, s4
	s_bfe_u32 s98, s32, 0x10006
	s_bfe_u32 s32, s32, 0x10007
	s_cmp_lg_u64 s[2:3], 0
	s_cselect_b32 s99, 1, 0
	s_xor_b32 s98, s98, s99
	s_or_b32 s99, s98, s32
	s_xor_b32 s32, s32, 1
	s_or_b32 s98, s98, s32
	s_cmp_eq_u32 s40, 0x7fffffff
	s_cselect_b32 s32, 0, s99
	s_cselect_b32 s98, 0, s98
	s_and_b32 s99, s32, s98
	s_cmp_lg_u64 s[78:79], 0
	s_cbranch_scc0 .Lsp_1163
	s_setprio 1

; #define PG8_BAR __builtin_amdgcn_s_barrier()
; template <class Epi, class Sched>
; __device__ __forceinline__ void gemm_phase(LAS unsigned char* lds, const GemmP g, const Sched& S, const Epi& E, int tid) {
;     ...
; #pragma unroll
;         for (int a = 0; a < 2; ++a)
; #pragma unroll
;             for (int b = 0; b < 2; ++b)
; #pragma unroll
;                 for (int m = 0; m < 4; ++m)
; #pragma unroll
;                     for (int n = 0; n < 2; ++n) acc[a][b][m][n] = (f32x4){0.f, 0.f, 0.f, 0.f};
;         cur = nxt; cA = nA; cB = nB; ++ui;
;         if (wr == 1) PG8_BAR;
.LBB0_1389:
	s_add_u32 s14, s12, 0x100
	s_addc_u32 s15, s13, 0
	s_add_u32 s6, s10, 0x40080
	v_mov_b32_e32 v96, 0
	s_addc_u32 s7, s11, 0
	s_mov_b32 s38, -2
	v_mov_b32_e32 v97, v96
	v_mov_b32_e32 v98, v96
	v_mov_b32_e32 v99, v96
	v_mov_b32_e32 v100, v96
	v_mov_b32_e32 v101, v96
	v_mov_b32_e32 v102, v96
	v_mov_b32_e32 v103, v96
	v_mov_b32_e32 v0, v96
	v_mov_b32_e32 v1, v96
	v_mov_b32_e32 v2, v96
	v_mov_b32_e32 v3, v96
	v_mov_b32_e32 v4, v96
	v_mov_b32_e32 v5, v96
	v_mov_b32_e32 v6, v96
	v_mov_b32_e32 v7, v96
	v_mov_b32_e32 v16, v96
	v_mov_b32_e32 v17, v96
	v_mov_b32_e32 v18, v96
	v_mov_b32_e32 v19, v96
	v_mov_b32_e32 v20, v96
	v_mov_b32_e32 v21, v96
	v_mov_b32_e32 v22, v96
	v_mov_b32_e32 v23, v96
	v_mov_b32_e32 v32, v96
	v_mov_b32_e32 v33, v96
	v_mov_b32_e32 v34, v96
	v_mov_b32_e32 v35, v96
	v_mov_b32_e32 v36, v96
	v_mov_b32_e32 v37, v96
	v_mov_b32_e32 v38, v96
	v_mov_b32_e32 v39, v96
	v_mov_b32_e32 v104, v96
	v_mov_b32_e32 v105, v96
	v_mov_b32_e32 v106, v96
	v_mov_b32_e32 v107, v96
	v_mov_b32_e32 v108, v96
	v_mov_b32_e32 v109, v96
	v_mov_b32_e32 v110, v96
	v_mov_b32_e32 v111, v96
	v_mov_b32_e32 v8, v96
	v_mov_b32_e32 v9, v96
	v_mov_b32_e32 v10, v96
	v_mov_b32_e32 v11, v96
	v_mov_b32_e32 v12, v96
	v_mov_b32_e32 v13, v96
	v_mov_b32_e32 v14, v96
	v_mov_b32_e32 v15, v96
	v_mov_b32_e32 v24, v96
	v_mov_b32_e32 v25, v96
	v_mov_b32_e32 v26, v96
	v_mov_b32_e32 v27, v96
	v_mov_b32_e32 v28, v96
	v_mov_b32_e32 v29, v96
	v_mov_b32_e32 v30, v96
	v_mov_b32_e32 v31, v96
	v_mov_b32_e32 v40, v96
	v_mov_b32_e32 v41, v96
	v_mov_b32_e32 v42, v96
	v_mov_b32_e32 v43, v96
	v_mov_b32_e32 v44, v96
	v_mov_b32_e32 v45, v96
	v_mov_b32_e32 v46, v96
	v_mov_b32_e32 v47, v96
	v_mov_b32_e32 v112, v96
	v_mov_b32_e32 v113, v96
	v_mov_b32_e32 v114, v96
	v_mov_b32_e32 v115, v96
	v_mov_b32_e32 v116, v96
	v_mov_b32_e32 v117, v96
	v_mov_b32_e32 v118, v96
	v_mov_b32_e32 v119, v96
	v_mov_b32_e32 v48, v96
	v_mov_b32_e32 v49, v96
	v_mov_b32_e32 v50, v96
	v_mov_b32_e32 v51, v96
	v_mov_b32_e32 v52, v96
	v_mov_b32_e32 v53, v96
	v_mov_b32_e32 v54, v96
	v_mov_b32_e32 v55, v96
	v_mov_b32_e32 v64, v96
	v_mov_b32_e32 v65, v96
	v_mov_b32_e32 v66, v96
	v_mov_b32_e32 v67, v96
	v_mov_b32_e32 v68, v96
	v_mov_b32_e32 v69, v96
	v_mov_b32_e32 v70, v96
	v_mov_b32_e32 v71, v96
	v_mov_b32_e32 v80, v96
	v_mov_b32_e32 v81, v96
	v_mov_b32_e32 v82, v96
	v_mov_b32_e32 v83, v96
	v_mov_b32_e32 v84, v96
	v_mov_b32_e32 v85, v96
	v_mov_b32_e32 v86, v96
	v_mov_b32_e32 v87, v96
	v_mov_b32_e32 v120, v96
	v_mov_b32_e32 v121, v96
	v_mov_b32_e32 v122, v96
	v_mov_b32_e32 v123, v96
	v_mov_b32_e32 v124, v96
	v_mov_b32_e32 v125, v96
	v_mov_b32_e32 v126, v96
	v_mov_b32_e32 v127, v96
	v_mov_b32_e32 v56, v96
	v_mov_b32_e32 v57, v96
	v_mov_b32_e32 v58, v96
	v_mov_b32_e32 v59, v96
	v_mov_b32_e32 v60, v96
	v_mov_b32_e32 v61, v96
	v_mov_b32_e32 v62, v96
	v_mov_b32_e32 v63, v96
	v_mov_b32_e32 v72, v96
	v_mov_b32_e32 v73, v96
	v_mov_b32_e32 v74, v96
	v_mov_b32_e32 v75, v96
	v_mov_b32_e32 v76, v96
	v_mov_b32_e32 v77, v96
	v_mov_b32_e32 v78, v96
	v_mov_b32_e32 v79, v96
	v_mov_b32_e32 v88, v96
	v_mov_b32_e32 v89, v96
	v_mov_b32_e32 v90, v96
	v_mov_b32_e32 v91, v96
	v_mov_b32_e32 v92, v96
	v_mov_b32_e32 v93, v96
	v_mov_b32_e32 v94, v96
	v_mov_b32_e32 v95, v96
	s_cmp_lg_u64 s[2:3], 0
	s_cbranch_scc0 .Lsp_1390
	s_setprio 1

; #define PG8_BAR __builtin_amdgcn_s_barrier()
; template <class Epi, class Sched>
; __device__ __forceinline__ void gemm_phase(LAS unsigned char* lds, const GemmP g, const Sched& S, const Epi& E, int tid) {
;     ...
; #pragma unroll
;         for (int a = 0; a < 2; ++a)
; #pragma unroll
;             for (int b = 0; b < 2; ++b)
; #pragma unroll
;                 for (int m = 0; m < 4; ++m)
; #pragma unroll
;                     for (int n = 0; n < 2; ++n) acc[a][b][m][n] = (f32x4){0.f, 0.f, 0.f, 0.f};
;         cur = nxt; cA = nA; cB = nB; ++ui;
;         if (wr == 1) PG8_BAR;
.LBB0_1533:
	s_add_u32 s16, s8, 0x100
	v_mov_b32_e32 v0, 0
	s_addc_u32 s17, s9, 0
	s_mov_b32 s18, -2
	v_mov_b32_e32 v1, v0
	v_mov_b32_e32 v2, v0
	s_waitcnt lgkmcnt(0)
	v_mov_b32_e32 v3, v0
	v_mov_b32_e32 v4, v0
	v_mov_b32_e32 v5, v0
	v_mov_b32_e32 v6, v0
	v_mov_b32_e32 v7, v0
	v_mov_b32_e32 v8, v0
	v_mov_b32_e32 v9, v0
	v_mov_b32_e32 v10, v0
	v_mov_b32_e32 v11, v0
	v_mov_b32_e32 v12, v0
	v_mov_b32_e32 v13, v0
	v_mov_b32_e32 v14, v0
	v_mov_b32_e32 v15, v0
	v_mov_b32_e32 v16, v0
	v_mov_b32_e32 v17, v0
	v_mov_b32_e32 v18, v0
	v_mov_b32_e32 v19, v0
	v_mov_b32_e32 v20, v0
	v_mov_b32_e32 v21, v0
	v_mov_b32_e32 v22, v0
	v_mov_b32_e32 v23, v0
	v_mov_b32_e32 v24, v0
	v_mov_b32_e32 v25, v0
	v_mov_b32_e32 v26, v0
	v_mov_b32_e32 v27, v0
	v_mov_b32_e32 v28, v0
	v_mov_b32_e32 v29, v0
	v_mov_b32_e32 v30, v0
	v_mov_b32_e32 v31, v0
	v_mov_b32_e32 v56, v0
	v_mov_b32_e32 v57, v0
	v_mov_b32_e32 v58, v0
	v_mov_b32_e32 v59, v0
	v_mov_b32_e32 v64, v0
	v_mov_b32_e32 v65, v0
	v_mov_b32_e32 v66, v0
	v_mov_b32_e32 v67, v0
	v_mov_b32_e32 v72, v0
	v_mov_b32_e32 v73, v0
	v_mov_b32_e32 v74, v0
	v_mov_b32_e32 v75, v0
	v_mov_b32_e32 v76, v0
	v_mov_b32_e32 v77, v0
	v_mov_b32_e32 v78, v0
	v_mov_b32_e32 v79, v0
	v_mov_b32_e32 v80, v0
	v_mov_b32_e32 v81, v0
	v_mov_b32_e32 v82, v0
	v_mov_b32_e32 v83, v0
	v_mov_b32_e32 v84, v0
	v_mov_b32_e32 v85, v0
	v_mov_b32_e32 v86, v0
	v_mov_b32_e32 v87, v0
	v_mov_b32_e32 v88, v0
	v_mov_b32_e32 v89, v0
	v_mov_b32_e32 v90, v0
	v_mov_b32_e32 v91, v0
	v_mov_b32_e32 v92, v0
	v_mov_b32_e32 v93, v0
	v_mov_b32_e32 v94, v0
	v_mov_b32_e32 v95, v0
	v_mov_b32_e32 v32, v0
	v_mov_b32_e32 v33, v0
	v_mov_b32_e32 v34, v0
	v_mov_b32_e32 v35, v0
	v_mov_b32_e32 v36, v0
	v_mov_b32_e32 v37, v0
	v_mov_b32_e32 v38, v0
	v_mov_b32_e32 v39, v0
	v_mov_b32_e32 v40, v0
	v_mov_b32_e32 v41, v0
	v_mov_b32_e32 v42, v0
	v_mov_b32_e32 v43, v0
	v_mov_b32_e32 v44, v0
	v_mov_b32_e32 v45, v0
	v_mov_b32_e32 v46, v0
	v_mov_b32_e32 v47, v0
	v_mov_b32_e32 v48, v0
	v_mov_b32_e32 v49, v0
	v_mov_b32_e32 v50, v0
	v_mov_b32_e32 v51, v0
	v_mov_b32_e32 v52, v0
	v_mov_b32_e32 v53, v0
	v_mov_b32_e32 v54, v0
	v_mov_b32_e32 v55, v0
	v_mov_b32_e32 v60, v0
	v_mov_b32_e32 v61, v0
	v_mov_b32_e32 v62, v0
	v_mov_b32_e32 v63, v0
	v_mov_b32_e32 v68, v0
	v_mov_b32_e32 v69, v0
	v_mov_b32_e32 v70, v0
	v_mov_b32_e32 v71, v0
	v_mov_b32_e32 v96, v0
	v_mov_b32_e32 v97, v0
	v_mov_b32_e32 v98, v0
	v_mov_b32_e32 v99, v0
	v_mov_b32_e32 v100, v0
	v_mov_b32_e32 v101, v0
	v_mov_b32_e32 v102, v0
	v_mov_b32_e32 v103, v0
	v_mov_b32_e32 v104, v0
	v_mov_b32_e32 v105, v0
	v_mov_b32_e32 v106, v0
	v_mov_b32_e32 v107, v0
	v_mov_b32_e32 v108, v0
	v_mov_b32_e32 v109, v0
	v_mov_b32_e32 v110, v0
	v_mov_b32_e32 v111, v0
	v_mov_b32_e32 v112, v0
	v_mov_b32_e32 v113, v0
	v_mov_b32_e32 v114, v0
	v_mov_b32_e32 v115, v0
	v_mov_b32_e32 v116, v0
	v_mov_b32_e32 v117, v0
	v_mov_b32_e32 v118, v0
	v_mov_b32_e32 v119, v0
	v_mov_b32_e32 v120, v0
	v_mov_b32_e32 v121, v0
	v_mov_b32_e32 v122, v0
	v_mov_b32_e32 v123, v0
	v_mov_b32_e32 v124, v0
	v_mov_b32_e32 v125, v0
	v_mov_b32_e32 v126, v0
	v_mov_b32_e32 v127, v0
	s_cmp_lg_u64 s[86:87], 0
	s_cbranch_scc0 .Lsp_1534
	s_setprio 1
